# gates GEMV loop fully unrolled: activation batch prefetched one batch ahead, all 16 weight fragments in flight (was 2)
# speedup vs baseline: 1.0221x; 1.0002x over previous
.LBB0_161:
	v_ashrrev_i32_e32 v15, 31, v14
	v_lshlrev_b64 v[2:3], 13, v[14:15]
	v_lshl_add_u64 v[18:19], v[12:13], 0, v[2:3]
	s_mov_b64 s[0:1], 0
	v_mov_b32_e32 v2, 0
	v_mov_b32_e32 v3, v7
	v_mov_b32_e32 v4, v7
	v_mov_b32_e32 v5, v7
	s_waitcnt vmcnt(0)
	v_add_co_u32_e32 v90, vcc, 0x11001000, v18
	s_nop 1
	v_addc_co_u32_e32 v91, vcc, 0, v19, vcc
	v_add_co_u32_e32 v92, vcc, 0x101000, v16
	s_nop 1
	v_addc_co_u32_e32 v93, vcc, 0, v17, vcc
	global_load_dwordx4 v[22:25], v[90:91], off offset:-4096
	global_load_dwordx4 v[26:29], v[90:91], off offset:-4032
	global_load_dwordx4 v[30:33], v[90:91], off offset:-3968
	global_load_dwordx4 v[34:37], v[90:91], off offset:-3904
	global_load_dwordx4 v[38:41], v[90:91], off offset:-3840
	global_load_dwordx4 v[42:45], v[90:91], off offset:-3776
	global_load_dwordx4 v[46:49], v[90:91], off offset:-3712
	global_load_dwordx4 v[50:53], v[90:91], off offset:-3648
	global_load_dwordx4 v[54:57], v[90:91], off offset:-3584
	global_load_dwordx4 v[58:61], v[90:91], off offset:-3520
	global_load_dwordx4 v[62:65], v[90:91], off offset:-3456
	global_load_dwordx4 v[66:69], v[90:91], off offset:-3392
	global_load_dwordx4 v[70:73], v[90:91], off offset:-3328
	global_load_dwordx4 v[74:77], v[90:91], off offset:-3264
	global_load_dwordx4 v[78:81], v[90:91], off offset:-3200
	global_load_dwordx4 v[82:85], v[90:91], off offset:-3136
	global_load_dwordx4 v[164:167], v[92:93], off offset:-4096
	global_load_dwordx4 v[168:171], v[92:93], off offset:-4032
	global_load_dwordx4 v[172:175], v[92:93], off offset:-3968
	global_load_dwordx4 v[176:179], v[92:93], off offset:-3904
	global_load_dwordx4 v[184:187], v[92:93], off offset:-3840
	global_load_dwordx4 v[188:191], v[92:93], off offset:-3776
	global_load_dwordx4 v[192:195], v[92:93], off offset:-3712
	global_load_dwordx4 v[196:199], v[92:93], off offset:-3648
	global_load_dwordx4 v[200:203], v[92:93], off offset:-3584
	global_load_dwordx4 v[204:207], v[92:93], off offset:-3520
	global_load_dwordx4 v[208:211], v[92:93], off offset:-3456
	global_load_dwordx4 v[212:215], v[92:93], off offset:-3392
	global_load_dwordx4 v[216:219], v[92:93], off offset:-3328
	global_load_dwordx4 v[220:223], v[92:93], off offset:-3264
	global_load_dwordx4 v[224:227], v[92:93], off offset:-3200
	global_load_dwordx4 v[228:231], v[92:93], off offset:-3136
	global_load_dwordx4 v[94:97], v[90:91], off offset:-3072
	global_load_dwordx4 v[98:101], v[90:91], off offset:-3008
	global_load_dwordx4 v[102:105], v[90:91], off offset:-2944
	global_load_dwordx4 v[106:109], v[90:91], off offset:-2880
	global_load_dwordx4 v[110:113], v[90:91], off offset:-2816
	global_load_dwordx4 v[114:117], v[90:91], off offset:-2752
	global_load_dwordx4 v[118:121], v[90:91], off offset:-2688
	global_load_dwordx4 v[122:125], v[90:91], off offset:-2624
	global_load_dwordx4 v[126:129], v[90:91], off offset:-2560
	global_load_dwordx4 v[130:133], v[90:91], off offset:-2496
	global_load_dwordx4 v[134:137], v[90:91], off offset:-2432
	global_load_dwordx4 v[140:143], v[90:91], off offset:-2368
	global_load_dwordx4 v[144:147], v[90:91], off offset:-2304
	global_load_dwordx4 v[148:151], v[90:91], off offset:-2240
	global_load_dwordx4 v[152:155], v[90:91], off offset:-2176
	global_load_dwordx4 v[156:159], v[90:91], off offset:-2112
	s_waitcnt vmcnt(31)
	v_mfma_f32_16x16x32_bf16 v[2:5], v[22:25], v[164:167], v[2:5]
	global_load_dwordx4 v[164:167], v[92:93], off offset:-3072
	s_waitcnt vmcnt(31)
	v_mfma_f32_16x16x32_bf16 v[2:5], v[26:29], v[168:171], v[2:5]
	global_load_dwordx4 v[168:171], v[92:93], off offset:-3008
	s_waitcnt vmcnt(31)
	v_mfma_f32_16x16x32_bf16 v[2:5], v[30:33], v[172:175], v[2:5]
	global_load_dwordx4 v[172:175], v[92:93], off offset:-2944
	s_waitcnt vmcnt(31)
	v_mfma_f32_16x16x32_bf16 v[2:5], v[34:37], v[176:179], v[2:5]
	global_load_dwordx4 v[176:179], v[92:93], off offset:-2880
	s_waitcnt vmcnt(31)
	v_mfma_f32_16x16x32_bf16 v[2:5], v[38:41], v[184:187], v[2:5]
	global_load_dwordx4 v[184:187], v[92:93], off offset:-2816
	s_waitcnt vmcnt(31)
	v_mfma_f32_16x16x32_bf16 v[2:5], v[42:45], v[188:191], v[2:5]
	global_load_dwordx4 v[188:191], v[92:93], off offset:-2752
	s_waitcnt vmcnt(31)
	v_mfma_f32_16x16x32_bf16 v[2:5], v[46:49], v[192:195], v[2:5]
	global_load_dwordx4 v[192:195], v[92:93], off offset:-2688
	s_waitcnt vmcnt(31)
	v_mfma_f32_16x16x32_bf16 v[2:5], v[50:53], v[196:199], v[2:5]
	global_load_dwordx4 v[196:199], v[92:93], off offset:-2624
	s_waitcnt vmcnt(31)
	v_mfma_f32_16x16x32_bf16 v[2:5], v[54:57], v[200:203], v[2:5]
	global_load_dwordx4 v[200:203], v[92:93], off offset:-2560
	s_waitcnt vmcnt(31)
	v_mfma_f32_16x16x32_bf16 v[2:5], v[58:61], v[204:207], v[2:5]
	global_load_dwordx4 v[204:207], v[92:93], off offset:-2496
	s_waitcnt vmcnt(31)
	v_mfma_f32_16x16x32_bf16 v[2:5], v[62:65], v[208:211], v[2:5]
	global_load_dwordx4 v[208:211], v[92:93], off offset:-2432
	s_waitcnt vmcnt(31)
	v_mfma_f32_16x16x32_bf16 v[2:5], v[66:69], v[212:215], v[2:5]
	global_load_dwordx4 v[212:215], v[92:93], off offset:-2368
	s_waitcnt vmcnt(31)
	v_mfma_f32_16x16x32_bf16 v[2:5], v[70:73], v[216:219], v[2:5]
	global_load_dwordx4 v[216:219], v[92:93], off offset:-2304
	s_waitcnt vmcnt(31)
	v_mfma_f32_16x16x32_bf16 v[2:5], v[74:77], v[220:223], v[2:5]
	global_load_dwordx4 v[220:223], v[92:93], off offset:-2240
	s_waitcnt vmcnt(31)
	v_mfma_f32_16x16x32_bf16 v[2:5], v[78:81], v[224:227], v[2:5]
	global_load_dwordx4 v[224:227], v[92:93], off offset:-2176
	s_waitcnt vmcnt(31)
	v_mfma_f32_16x16x32_bf16 v[2:5], v[82:85], v[228:231], v[2:5]
	global_load_dwordx4 v[228:231], v[92:93], off offset:-2112
	global_load_dwordx4 v[22:25], v[90:91], off offset:-2048
	global_load_dwordx4 v[26:29], v[90:91], off offset:-1984
	global_load_dwordx4 v[30:33], v[90:91], off offset:-1920
	global_load_dwordx4 v[34:37], v[90:91], off offset:-1856
	global_load_dwordx4 v[38:41], v[90:91], off offset:-1792
	global_load_dwordx4 v[42:45], v[90:91], off offset:-1728
	global_load_dwordx4 v[46:49], v[90:91], off offset:-1664
	global_load_dwordx4 v[50:53], v[90:91], off offset:-1600
	global_load_dwordx4 v[54:57], v[90:91], off offset:-1536
	global_load_dwordx4 v[58:61], v[90:91], off offset:-1472
	global_load_dwordx4 v[62:65], v[90:91], off offset:-1408
	global_load_dwordx4 v[66:69], v[90:91], off offset:-1344
	global_load_dwordx4 v[70:73], v[90:91], off offset:-1280
	global_load_dwordx4 v[74:77], v[90:91], off offset:-1216
	global_load_dwordx4 v[78:81], v[90:91], off offset:-1152
	global_load_dwordx4 v[82:85], v[90:91], off offset:-1088
	s_waitcnt vmcnt(31)
	v_mfma_f32_16x16x32_bf16 v[2:5], v[94:97], v[164:167], v[2:5]
	global_load_dwordx4 v[164:167], v[92:93], off offset:-2048
	s_waitcnt vmcnt(31)
	v_mfma_f32_16x16x32_bf16 v[2:5], v[98:101], v[168:171], v[2:5]
	global_load_dwordx4 v[168:171], v[92:93], off offset:-1984
	s_waitcnt vmcnt(31)
	v_mfma_f32_16x16x32_bf16 v[2:5], v[102:105], v[172:175], v[2:5]
	global_load_dwordx4 v[172:175], v[92:93], off offset:-1920
	s_waitcnt vmcnt(31)
	v_mfma_f32_16x16x32_bf16 v[2:5], v[106:109], v[176:179], v[2:5]
	global_load_dwordx4 v[176:179], v[92:93], off offset:-1856
	s_waitcnt vmcnt(31)
	v_mfma_f32_16x16x32_bf16 v[2:5], v[110:113], v[184:187], v[2:5]
	global_load_dwordx4 v[184:187], v[92:93], off offset:-1792
	s_waitcnt vmcnt(31)
	v_mfma_f32_16x16x32_bf16 v[2:5], v[114:117], v[188:191], v[2:5]
	global_load_dwordx4 v[188:191], v[92:93], off offset:-1728
	s_waitcnt vmcnt(31)
	v_mfma_f32_16x16x32_bf16 v[2:5], v[118:121], v[192:195], v[2:5]
	global_load_dwordx4 v[192:195], v[92:93], off offset:-1664
	s_waitcnt vmcnt(31)
	v_mfma_f32_16x16x32_bf16 v[2:5], v[122:125], v[196:199], v[2:5]
	global_load_dwordx4 v[196:199], v[92:93], off offset:-1600
	s_waitcnt vmcnt(31)
	v_mfma_f32_16x16x32_bf16 v[2:5], v[126:129], v[200:203], v[2:5]
	global_load_dwordx4 v[200:203], v[92:93], off offset:-1536
	s_waitcnt vmcnt(31)
	v_mfma_f32_16x16x32_bf16 v[2:5], v[130:133], v[204:207], v[2:5]
	global_load_dwordx4 v[204:207], v[92:93], off offset:-1472
	s_waitcnt vmcnt(31)
	v_mfma_f32_16x16x32_bf16 v[2:5], v[134:137], v[208:211], v[2:5]
	global_load_dwordx4 v[208:211], v[92:93], off offset:-1408
	s_waitcnt vmcnt(31)
	v_mfma_f32_16x16x32_bf16 v[2:5], v[140:143], v[212:215], v[2:5]
	global_load_dwordx4 v[212:215], v[92:93], off offset:-1344
	s_waitcnt vmcnt(31)
	v_mfma_f32_16x16x32_bf16 v[2:5], v[144:147], v[216:219], v[2:5]
	global_load_dwordx4 v[216:219], v[92:93], off offset:-1280
	s_waitcnt vmcnt(31)
	v_mfma_f32_16x16x32_bf16 v[2:5], v[148:151], v[220:223], v[2:5]
	global_load_dwordx4 v[220:223], v[92:93], off offset:-1216
	s_waitcnt vmcnt(31)
	v_mfma_f32_16x16x32_bf16 v[2:5], v[152:155], v[224:227], v[2:5]
	global_load_dwordx4 v[224:227], v[92:93], off offset:-1152
	s_waitcnt vmcnt(31)
	v_mfma_f32_16x16x32_bf16 v[2:5], v[156:159], v[228:231], v[2:5]
	global_load_dwordx4 v[228:231], v[92:93], off offset:-1088
	global_load_dwordx4 v[94:97], v[90:91], off offset:-1024
	global_load_dwordx4 v[98:101], v[90:91], off offset:-960
	global_load_dwordx4 v[102:105], v[90:91], off offset:-896
	global_load_dwordx4 v[106:109], v[90:91], off offset:-832
	global_load_dwordx4 v[110:113], v[90:91], off offset:-768
	global_load_dwordx4 v[114:117], v[90:91], off offset:-704
	global_load_dwordx4 v[118:121], v[90:91], off offset:-640
	global_load_dwordx4 v[122:125], v[90:91], off offset:-576
	global_load_dwordx4 v[126:129], v[90:91], off offset:-512
	global_load_dwordx4 v[130:133], v[90:91], off offset:-448
	global_load_dwordx4 v[134:137], v[90:91], off offset:-384
	global_load_dwordx4 v[140:143], v[90:91], off offset:-320
	global_load_dwordx4 v[144:147], v[90:91], off offset:-256
	global_load_dwordx4 v[148:151], v[90:91], off offset:-192
	global_load_dwordx4 v[152:155], v[90:91], off offset:-128
	global_load_dwordx4 v[156:159], v[90:91], off offset:-64
	s_waitcnt vmcnt(31)
	v_mfma_f32_16x16x32_bf16 v[2:5], v[22:25], v[164:167], v[2:5]
	global_load_dwordx4 v[164:167], v[92:93], off offset:-1024
	s_waitcnt vmcnt(31)
	v_mfma_f32_16x16x32_bf16 v[2:5], v[26:29], v[168:171], v[2:5]
	global_load_dwordx4 v[168:171], v[92:93], off offset:-960
	s_waitcnt vmcnt(31)
	v_mfma_f32_16x16x32_bf16 v[2:5], v[30:33], v[172:175], v[2:5]
	global_load_dwordx4 v[172:175], v[92:93], off offset:-896
	s_waitcnt vmcnt(31)
	v_mfma_f32_16x16x32_bf16 v[2:5], v[34:37], v[176:179], v[2:5]
	global_load_dwordx4 v[176:179], v[92:93], off offset:-832
	s_waitcnt vmcnt(31)
	v_mfma_f32_16x16x32_bf16 v[2:5], v[38:41], v[184:187], v[2:5]
	global_load_dwordx4 v[184:187], v[92:93], off offset:-768
	s_waitcnt vmcnt(31)
	v_mfma_f32_16x16x32_bf16 v[2:5], v[42:45], v[188:191], v[2:5]
	global_load_dwordx4 v[188:191], v[92:93], off offset:-704
	s_waitcnt vmcnt(31)
	v_mfma_f32_16x16x32_bf16 v[2:5], v[46:49], v[192:195], v[2:5]
	global_load_dwordx4 v[192:195], v[92:93], off offset:-640
	s_waitcnt vmcnt(31)
	v_mfma_f32_16x16x32_bf16 v[2:5], v[50:53], v[196:199], v[2:5]
	global_load_dwordx4 v[196:199], v[92:93], off offset:-576
	s_waitcnt vmcnt(31)
	v_mfma_f32_16x16x32_bf16 v[2:5], v[54:57], v[200:203], v[2:5]
	global_load_dwordx4 v[200:203], v[92:93], off offset:-512
	s_waitcnt vmcnt(31)
	v_mfma_f32_16x16x32_bf16 v[2:5], v[58:61], v[204:207], v[2:5]
	global_load_dwordx4 v[204:207], v[92:93], off offset:-448
	s_waitcnt vmcnt(31)
	v_mfma_f32_16x16x32_bf16 v[2:5], v[62:65], v[208:211], v[2:5]
	global_load_dwordx4 v[208:211], v[92:93], off offset:-384
	s_waitcnt vmcnt(31)
	v_mfma_f32_16x16x32_bf16 v[2:5], v[66:69], v[212:215], v[2:5]
	global_load_dwordx4 v[212:215], v[92:93], off offset:-320
	s_waitcnt vmcnt(31)
	v_mfma_f32_16x16x32_bf16 v[2:5], v[70:73], v[216:219], v[2:5]
	global_load_dwordx4 v[216:219], v[92:93], off offset:-256
	s_waitcnt vmcnt(31)
	v_mfma_f32_16x16x32_bf16 v[2:5], v[74:77], v[220:223], v[2:5]
	global_load_dwordx4 v[220:223], v[92:93], off offset:-192
	s_waitcnt vmcnt(31)
	v_mfma_f32_16x16x32_bf16 v[2:5], v[78:81], v[224:227], v[2:5]
	global_load_dwordx4 v[224:227], v[92:93], off offset:-128
	s_waitcnt vmcnt(31)
	v_mfma_f32_16x16x32_bf16 v[2:5], v[82:85], v[228:231], v[2:5]
	global_load_dwordx4 v[228:231], v[92:93], off offset:-64
	global_load_dwordx4 v[22:25], v[90:91], off
	global_load_dwordx4 v[26:29], v[90:91], off offset:64
	global_load_dwordx4 v[30:33], v[90:91], off offset:128
	global_load_dwordx4 v[34:37], v[90:91], off offset:192
	global_load_dwordx4 v[38:41], v[90:91], off offset:256
	global_load_dwordx4 v[42:45], v[90:91], off offset:320
	global_load_dwordx4 v[46:49], v[90:91], off offset:384
	global_load_dwordx4 v[50:53], v[90:91], off offset:448
	global_load_dwordx4 v[54:57], v[90:91], off offset:512
	global_load_dwordx4 v[58:61], v[90:91], off offset:576
	global_load_dwordx4 v[62:65], v[90:91], off offset:640
	global_load_dwordx4 v[66:69], v[90:91], off offset:704
	global_load_dwordx4 v[70:73], v[90:91], off offset:768
	global_load_dwordx4 v[74:77], v[90:91], off offset:832
	global_load_dwordx4 v[78:81], v[90:91], off offset:896
	global_load_dwordx4 v[82:85], v[90:91], off offset:960
	s_waitcnt vmcnt(31)
	v_mfma_f32_16x16x32_bf16 v[2:5], v[94:97], v[164:167], v[2:5]
	global_load_dwordx4 v[164:167], v[92:93], off
	s_waitcnt vmcnt(31)
	v_mfma_f32_16x16x32_bf16 v[2:5], v[98:101], v[168:171], v[2:5]
	global_load_dwordx4 v[168:171], v[92:93], off offset:64
	s_waitcnt vmcnt(31)
	v_mfma_f32_16x16x32_bf16 v[2:5], v[102:105], v[172:175], v[2:5]
	global_load_dwordx4 v[172:175], v[92:93], off offset:128
	s_waitcnt vmcnt(31)
	v_mfma_f32_16x16x32_bf16 v[2:5], v[106:109], v[176:179], v[2:5]
	global_load_dwordx4 v[176:179], v[92:93], off offset:192
	s_waitcnt vmcnt(31)
	v_mfma_f32_16x16x32_bf16 v[2:5], v[110:113], v[184:187], v[2:5]
	global_load_dwordx4 v[184:187], v[92:93], off offset:256
	s_waitcnt vmcnt(31)
	v_mfma_f32_16x16x32_bf16 v[2:5], v[114:117], v[188:191], v[2:5]
	global_load_dwordx4 v[188:191], v[92:93], off offset:320
	s_waitcnt vmcnt(31)
	v_mfma_f32_16x16x32_bf16 v[2:5], v[118:121], v[192:195], v[2:5]
	global_load_dwordx4 v[192:195], v[92:93], off offset:384
	s_waitcnt vmcnt(31)
	v_mfma_f32_16x16x32_bf16 v[2:5], v[122:125], v[196:199], v[2:5]
	global_load_dwordx4 v[196:199], v[92:93], off offset:448
	s_waitcnt vmcnt(31)
	v_mfma_f32_16x16x32_bf16 v[2:5], v[126:129], v[200:203], v[2:5]
	global_load_dwordx4 v[200:203], v[92:93], off offset:512
	s_waitcnt vmcnt(31)
	v_mfma_f32_16x16x32_bf16 v[2:5], v[130:133], v[204:207], v[2:5]
	global_load_dwordx4 v[204:207], v[92:93], off offset:576
	s_waitcnt vmcnt(31)
	v_mfma_f32_16x16x32_bf16 v[2:5], v[134:137], v[208:211], v[2:5]
	global_load_dwordx4 v[208:211], v[92:93], off offset:640
	s_waitcnt vmcnt(31)
	v_mfma_f32_16x16x32_bf16 v[2:5], v[140:143], v[212:215], v[2:5]
	global_load_dwordx4 v[212:215], v[92:93], off offset:704
	s_waitcnt vmcnt(31)
	v_mfma_f32_16x16x32_bf16 v[2:5], v[144:147], v[216:219], v[2:5]
	global_load_dwordx4 v[216:219], v[92:93], off offset:768
	s_waitcnt vmcnt(31)
	v_mfma_f32_16x16x32_bf16 v[2:5], v[148:151], v[220:223], v[2:5]
	global_load_dwordx4 v[220:223], v[92:93], off offset:832
	s_waitcnt vmcnt(31)
	v_mfma_f32_16x16x32_bf16 v[2:5], v[152:155], v[224:227], v[2:5]
	global_load_dwordx4 v[224:227], v[92:93], off offset:896
	s_waitcnt vmcnt(31)
	v_mfma_f32_16x16x32_bf16 v[2:5], v[156:159], v[228:231], v[2:5]
	global_load_dwordx4 v[228:231], v[92:93], off offset:960
	global_load_dwordx4 v[94:97], v[90:91], off offset:1024
	global_load_dwordx4 v[98:101], v[90:91], off offset:1088
	global_load_dwordx4 v[102:105], v[90:91], off offset:1152
	global_load_dwordx4 v[106:109], v[90:91], off offset:1216
	global_load_dwordx4 v[110:113], v[90:91], off offset:1280
	global_load_dwordx4 v[114:117], v[90:91], off offset:1344
	global_load_dwordx4 v[118:121], v[90:91], off offset:1408
	global_load_dwordx4 v[122:125], v[90:91], off offset:1472
	global_load_dwordx4 v[126:129], v[90:91], off offset:1536
	global_load_dwordx4 v[130:133], v[90:91], off offset:1600
	global_load_dwordx4 v[134:137], v[90:91], off offset:1664
	global_load_dwordx4 v[140:143], v[90:91], off offset:1728
	global_load_dwordx4 v[144:147], v[90:91], off offset:1792
	global_load_dwordx4 v[148:151], v[90:91], off offset:1856
	global_load_dwordx4 v[152:155], v[90:91], off offset:1920
	global_load_dwordx4 v[156:159], v[90:91], off offset:1984
	s_waitcnt vmcnt(31)
	v_mfma_f32_16x16x32_bf16 v[2:5], v[22:25], v[164:167], v[2:5]
	global_load_dwordx4 v[164:167], v[92:93], off offset:1024
	s_waitcnt vmcnt(31)
	v_mfma_f32_16x16x32_bf16 v[2:5], v[26:29], v[168:171], v[2:5]
	global_load_dwordx4 v[168:171], v[92:93], off offset:1088
	s_waitcnt vmcnt(31)
	v_mfma_f32_16x16x32_bf16 v[2:5], v[30:33], v[172:175], v[2:5]
	global_load_dwordx4 v[172:175], v[92:93], off offset:1152
	s_waitcnt vmcnt(31)
	v_mfma_f32_16x16x32_bf16 v[2:5], v[34:37], v[176:179], v[2:5]
	global_load_dwordx4 v[176:179], v[92:93], off offset:1216
	s_waitcnt vmcnt(31)
	v_mfma_f32_16x16x32_bf16 v[2:5], v[38:41], v[184:187], v[2:5]
	global_load_dwordx4 v[184:187], v[92:93], off offset:1280
	s_waitcnt vmcnt(31)
	v_mfma_f32_16x16x32_bf16 v[2:5], v[42:45], v[188:191], v[2:5]
	global_load_dwordx4 v[188:191], v[92:93], off offset:1344
	s_waitcnt vmcnt(31)
	v_mfma_f32_16x16x32_bf16 v[2:5], v[46:49], v[192:195], v[2:5]
	global_load_dwordx4 v[192:195], v[92:93], off offset:1408
	s_waitcnt vmcnt(31)
	v_mfma_f32_16x16x32_bf16 v[2:5], v[50:53], v[196:199], v[2:5]
	global_load_dwordx4 v[196:199], v[92:93], off offset:1472
	s_waitcnt vmcnt(31)
	v_mfma_f32_16x16x32_bf16 v[2:5], v[54:57], v[200:203], v[2:5]
	global_load_dwordx4 v[200:203], v[92:93], off offset:1536
	s_waitcnt vmcnt(31)
	v_mfma_f32_16x16x32_bf16 v[2:5], v[58:61], v[204:207], v[2:5]
	global_load_dwordx4 v[204:207], v[92:93], off offset:1600
	s_waitcnt vmcnt(31)
	v_mfma_f32_16x16x32_bf16 v[2:5], v[62:65], v[208:211], v[2:5]
	global_load_dwordx4 v[208:211], v[92:93], off offset:1664
	s_waitcnt vmcnt(31)
	v_mfma_f32_16x16x32_bf16 v[2:5], v[66:69], v[212:215], v[2:5]
	global_load_dwordx4 v[212:215], v[92:93], off offset:1728
	s_waitcnt vmcnt(31)
	v_mfma_f32_16x16x32_bf16 v[2:5], v[70:73], v[216:219], v[2:5]
	global_load_dwordx4 v[216:219], v[92:93], off offset:1792
	s_waitcnt vmcnt(31)
	v_mfma_f32_16x16x32_bf16 v[2:5], v[74:77], v[220:223], v[2:5]
	global_load_dwordx4 v[220:223], v[92:93], off offset:1856
	s_waitcnt vmcnt(31)
	v_mfma_f32_16x16x32_bf16 v[2:5], v[78:81], v[224:227], v[2:5]
	global_load_dwordx4 v[224:227], v[92:93], off offset:1920
	s_waitcnt vmcnt(31)
	v_mfma_f32_16x16x32_bf16 v[2:5], v[82:85], v[228:231], v[2:5]
	global_load_dwordx4 v[228:231], v[92:93], off offset:1984
	global_load_dwordx4 v[22:25], v[90:91], off offset:2048
	global_load_dwordx4 v[26:29], v[90:91], off offset:2112
	global_load_dwordx4 v[30:33], v[90:91], off offset:2176
	global_load_dwordx4 v[34:37], v[90:91], off offset:2240
	global_load_dwordx4 v[38:41], v[90:91], off offset:2304
	global_load_dwordx4 v[42:45], v[90:91], off offset:2368
	global_load_dwordx4 v[46:49], v[90:91], off offset:2432
	global_load_dwordx4 v[50:53], v[90:91], off offset:2496
	global_load_dwordx4 v[54:57], v[90:91], off offset:2560
	global_load_dwordx4 v[58:61], v[90:91], off offset:2624
	global_load_dwordx4 v[62:65], v[90:91], off offset:2688
	global_load_dwordx4 v[66:69], v[90:91], off offset:2752
	global_load_dwordx4 v[70:73], v[90:91], off offset:2816
	global_load_dwordx4 v[74:77], v[90:91], off offset:2880
	global_load_dwordx4 v[78:81], v[90:91], off offset:2944
	global_load_dwordx4 v[82:85], v[90:91], off offset:3008
	s_waitcnt vmcnt(31)
	v_mfma_f32_16x16x32_bf16 v[2:5], v[94:97], v[164:167], v[2:5]
	global_load_dwordx4 v[164:167], v[92:93], off offset:2048
	s_waitcnt vmcnt(31)
	v_mfma_f32_16x16x32_bf16 v[2:5], v[98:101], v[168:171], v[2:5]
	global_load_dwordx4 v[168:171], v[92:93], off offset:2112
	s_waitcnt vmcnt(31)
	v_mfma_f32_16x16x32_bf16 v[2:5], v[102:105], v[172:175], v[2:5]
	global_load_dwordx4 v[172:175], v[92:93], off offset:2176
	s_waitcnt vmcnt(31)
	v_mfma_f32_16x16x32_bf16 v[2:5], v[106:109], v[176:179], v[2:5]
	global_load_dwordx4 v[176:179], v[92:93], off offset:2240
	s_waitcnt vmcnt(31)
	v_mfma_f32_16x16x32_bf16 v[2:5], v[110:113], v[184:187], v[2:5]
	global_load_dwordx4 v[184:187], v[92:93], off offset:2304
	s_waitcnt vmcnt(31)
	v_mfma_f32_16x16x32_bf16 v[2:5], v[114:117], v[188:191], v[2:5]
	global_load_dwordx4 v[188:191], v[92:93], off offset:2368
	s_waitcnt vmcnt(31)
	v_mfma_f32_16x16x32_bf16 v[2:5], v[118:121], v[192:195], v[2:5]
	global_load_dwordx4 v[192:195], v[92:93], off offset:2432
	s_waitcnt vmcnt(31)
	v_mfma_f32_16x16x32_bf16 v[2:5], v[122:125], v[196:199], v[2:5]
	global_load_dwordx4 v[196:199], v[92:93], off offset:2496
	s_waitcnt vmcnt(31)
	v_mfma_f32_16x16x32_bf16 v[2:5], v[126:129], v[200:203], v[2:5]
	global_load_dwordx4 v[200:203], v[92:93], off offset:2560
	s_waitcnt vmcnt(31)
	v_mfma_f32_16x16x32_bf16 v[2:5], v[130:133], v[204:207], v[2:5]
	global_load_dwordx4 v[204:207], v[92:93], off offset:2624
	s_waitcnt vmcnt(31)
	v_mfma_f32_16x16x32_bf16 v[2:5], v[134:137], v[208:211], v[2:5]
	global_load_dwordx4 v[208:211], v[92:93], off offset:2688
	s_waitcnt vmcnt(31)
	v_mfma_f32_16x16x32_bf16 v[2:5], v[140:143], v[212:215], v[2:5]
	global_load_dwordx4 v[212:215], v[92:93], off offset:2752
	s_waitcnt vmcnt(31)
	v_mfma_f32_16x16x32_bf16 v[2:5], v[144:147], v[216:219], v[2:5]
	global_load_dwordx4 v[216:219], v[92:93], off offset:2816
	s_waitcnt vmcnt(31)
	v_mfma_f32_16x16x32_bf16 v[2:5], v[148:151], v[220:223], v[2:5]
	global_load_dwordx4 v[220:223], v[92:93], off offset:2880
	s_waitcnt vmcnt(31)
	v_mfma_f32_16x16x32_bf16 v[2:5], v[152:155], v[224:227], v[2:5]
	global_load_dwordx4 v[224:227], v[92:93], off offset:2944
	s_waitcnt vmcnt(31)
	v_mfma_f32_16x16x32_bf16 v[2:5], v[156:159], v[228:231], v[2:5]
	global_load_dwordx4 v[228:231], v[92:93], off offset:3008
	global_load_dwordx4 v[94:97], v[90:91], off offset:3072
	global_load_dwordx4 v[98:101], v[90:91], off offset:3136
	global_load_dwordx4 v[102:105], v[90:91], off offset:3200
	global_load_dwordx4 v[106:109], v[90:91], off offset:3264
	global_load_dwordx4 v[110:113], v[90:91], off offset:3328
	global_load_dwordx4 v[114:117], v[90:91], off offset:3392
	global_load_dwordx4 v[118:121], v[90:91], off offset:3456
	global_load_dwordx4 v[122:125], v[90:91], off offset:3520
	global_load_dwordx4 v[126:129], v[90:91], off offset:3584
	global_load_dwordx4 v[130:133], v[90:91], off offset:3648
	global_load_dwordx4 v[134:137], v[90:91], off offset:3712
	global_load_dwordx4 v[140:143], v[90:91], off offset:3776
	global_load_dwordx4 v[144:147], v[90:91], off offset:3840
	global_load_dwordx4 v[148:151], v[90:91], off offset:3904
	global_load_dwordx4 v[152:155], v[90:91], off offset:3968
	global_load_dwordx4 v[156:159], v[90:91], off offset:4032
	s_waitcnt vmcnt(31)
	v_mfma_f32_16x16x32_bf16 v[2:5], v[22:25], v[164:167], v[2:5]
	global_load_dwordx4 v[164:167], v[92:93], off offset:3072
	s_waitcnt vmcnt(31)
	v_mfma_f32_16x16x32_bf16 v[2:5], v[26:29], v[168:171], v[2:5]
	global_load_dwordx4 v[168:171], v[92:93], off offset:3136
	s_waitcnt vmcnt(31)
	v_mfma_f32_16x16x32_bf16 v[2:5], v[30:33], v[172:175], v[2:5]
	global_load_dwordx4 v[172:175], v[92:93], off offset:3200
	s_waitcnt vmcnt(31)
	v_mfma_f32_16x16x32_bf16 v[2:5], v[34:37], v[176:179], v[2:5]
	global_load_dwordx4 v[176:179], v[92:93], off offset:3264
	s_waitcnt vmcnt(31)
	v_mfma_f32_16x16x32_bf16 v[2:5], v[38:41], v[184:187], v[2:5]
	global_load_dwordx4 v[184:187], v[92:93], off offset:3328
	s_waitcnt vmcnt(31)
	v_mfma_f32_16x16x32_bf16 v[2:5], v[42:45], v[188:191], v[2:5]
	global_load_dwordx4 v[188:191], v[92:93], off offset:3392
	s_waitcnt vmcnt(31)
	v_mfma_f32_16x16x32_bf16 v[2:5], v[46:49], v[192:195], v[2:5]
	global_load_dwordx4 v[192:195], v[92:93], off offset:3456
	s_waitcnt vmcnt(31)
	v_mfma_f32_16x16x32_bf16 v[2:5], v[50:53], v[196:199], v[2:5]
	global_load_dwordx4 v[196:199], v[92:93], off offset:3520
	s_waitcnt vmcnt(31)
	v_mfma_f32_16x16x32_bf16 v[2:5], v[54:57], v[200:203], v[2:5]
	global_load_dwordx4 v[200:203], v[92:93], off offset:3584
	s_waitcnt vmcnt(31)
	v_mfma_f32_16x16x32_bf16 v[2:5], v[58:61], v[204:207], v[2:5]
	global_load_dwordx4 v[204:207], v[92:93], off offset:3648
	s_waitcnt vmcnt(31)
	v_mfma_f32_16x16x32_bf16 v[2:5], v[62:65], v[208:211], v[2:5]
	global_load_dwordx4 v[208:211], v[92:93], off offset:3712
	s_waitcnt vmcnt(31)
	v_mfma_f32_16x16x32_bf16 v[2:5], v[66:69], v[212:215], v[2:5]
	global_load_dwordx4 v[212:215], v[92:93], off offset:3776
	s_waitcnt vmcnt(31)
	v_mfma_f32_16x16x32_bf16 v[2:5], v[70:73], v[216:219], v[2:5]
	global_load_dwordx4 v[216:219], v[92:93], off offset:3840
	s_waitcnt vmcnt(31)
	v_mfma_f32_16x16x32_bf16 v[2:5], v[74:77], v[220:223], v[2:5]
	global_load_dwordx4 v[220:223], v[92:93], off offset:3904
	s_waitcnt vmcnt(31)
	v_mfma_f32_16x16x32_bf16 v[2:5], v[78:81], v[224:227], v[2:5]
	global_load_dwordx4 v[224:227], v[92:93], off offset:3968
	s_waitcnt vmcnt(31)
	v_mfma_f32_16x16x32_bf16 v[2:5], v[82:85], v[228:231], v[2:5]
	global_load_dwordx4 v[228:231], v[92:93], off offset:4032
	s_waitcnt vmcnt(15)
	v_mfma_f32_16x16x32_bf16 v[2:5], v[94:97], v[164:167], v[2:5]
	s_waitcnt vmcnt(14)
	v_mfma_f32_16x16x32_bf16 v[2:5], v[98:101], v[168:171], v[2:5]
	s_waitcnt vmcnt(13)
	v_mfma_f32_16x16x32_bf16 v[2:5], v[102:105], v[172:175], v[2:5]
	s_waitcnt vmcnt(12)
	v_mfma_f32_16x16x32_bf16 v[2:5], v[106:109], v[176:179], v[2:5]
	s_waitcnt vmcnt(11)
	v_mfma_f32_16x16x32_bf16 v[2:5], v[110:113], v[184:187], v[2:5]
	s_waitcnt vmcnt(10)
	v_mfma_f32_16x16x32_bf16 v[2:5], v[114:117], v[188:191], v[2:5]
	s_waitcnt vmcnt(9)
	v_mfma_f32_16x16x32_bf16 v[2:5], v[118:121], v[192:195], v[2:5]
	s_waitcnt vmcnt(8)
	v_mfma_f32_16x16x32_bf16 v[2:5], v[122:125], v[196:199], v[2:5]
	s_waitcnt vmcnt(7)
	v_mfma_f32_16x16x32_bf16 v[2:5], v[126:129], v[200:203], v[2:5]
	s_waitcnt vmcnt(6)
	v_mfma_f32_16x16x32_bf16 v[2:5], v[130:133], v[204:207], v[2:5]
	s_waitcnt vmcnt(5)
	v_mfma_f32_16x16x32_bf16 v[2:5], v[134:137], v[208:211], v[2:5]
	s_waitcnt vmcnt(4)
	v_mfma_f32_16x16x32_bf16 v[2:5], v[140:143], v[212:215], v[2:5]
	s_waitcnt vmcnt(3)
	v_mfma_f32_16x16x32_bf16 v[2:5], v[144:147], v[216:219], v[2:5]
	s_waitcnt vmcnt(2)
	v_mfma_f32_16x16x32_bf16 v[2:5], v[148:151], v[220:223], v[2:5]
	s_waitcnt vmcnt(1)
	v_mfma_f32_16x16x32_bf16 v[2:5], v[152:155], v[224:227], v[2:5]
	s_waitcnt vmcnt(0)
	v_mfma_f32_16x16x32_bf16 v[2:5], v[156:159], v[228:231], v[2:5]
	global_load_dword v6, v[8:9], off
	s_lshl_b32 s0, s6, 6
	s_add_i32 s0, s0, s4
	v_or_b32_e32 v18, s0, v20
	v_ashrrev_i32_e32 v19, 31, v18
	v_or_b32_e32 v22, 1, v18
	v_or_b32_e32 v24, 2, v18
	v_or_b32_e32 v26, 3, v18
	s_add_i32 s6, s6, s33
	v_lshlrev_b64 v[18:19], 7, v[18:19]
	v_ashrrev_i32_e32 v23, 31, v22
	v_ashrrev_i32_e32 v25, 31, v24
	v_ashrrev_i32_e32 v27, 31, v26
	s_cmpk_gt_i32 s6, 0xff
	v_lshl_add_u64 v[18:19], v[10:11], 0, v[18:19]
	v_lshlrev_b64 v[22:23], 7, v[22:23]
	v_lshlrev_b64 v[24:25], 7, v[24:25]
	v_lshlrev_b64 v[26:27], 7, v[26:27]
	v_add_u32_e32 v14, s5, v14
	v_lshl_add_u64 v[22:23], v[10:11], 0, v[22:23]
	v_lshl_add_u64 v[24:25], v[10:11], 0, v[24:25]
	v_lshl_add_u64 v[26:27], v[10:11], 0, v[26:27]
	s_waitcnt vmcnt(0)
	v_add_f32_e32 v2, v2, v6
	v_add_f32_e32 v3, v3, v6
	v_add_f32_e32 v4, v4, v6
	v_add_f32_e32 v5, v5, v6
	global_store_dword v[18:19], v2, off
	global_store_dword v[22:23], v3, off
	global_store_dword v[24:25], v4, off
	global_store_dword v[26:27], v5, off
	s_cbranch_scc0 .LBB0_161
